# plus nontemporal LDS-DMA loads for the read-once A operand (ACT) of the down projection
# baseline (speedup 1.0000x reference)
; #define PG8_STAGE(bufoff, gbase, voff) do { _Pragma("unroll") for (int _i = 0; _i < 2; ++_i) \
;         glds_s((voff)[_i], (const void*)(gbase), ldsbase + (unsigned)((bufoff) + _i * 8192)); } while (0)
; #define PG8_LDA(dst, b, h) do { _Pragma("unroll") for (int m = 0; m < 4; ++m) _Pragma("unroll") for (int k = 0; k < 2; ++k) dst[m][k] = *(const LAS bf16x8*)(lds + PG8_SA(b, h) + aoff + m * 2048 + k * 1024); } while (0)
; #define PG8_LDB(dst, b, h) do { _Pragma("unroll") for (int n = 0; n < 2; ++n) _Pragma("unroll") for (int k = 0; k < 2; ++k) dst[n][k] = *(const LAS bf16x8*)(lds + PG8_SB(b, h) + boff + n * 2048 + k * 1024); } while (0)
; #define PG8_MMA(ai, bj, At, Bt) do { __builtin_amdgcn_s_setprio(1); _Pragma("unroll") for (int m = 0; m < 4; ++m) _Pragma("unroll") for (int n = 0; n < 2; ++n) _Pragma("unroll") for (int k = 0; k < 2; ++k) \
;         acc[ai][bj][m][n] = __builtin_amdgcn_mfma_f32_16x16x32_bf16(Bt[n][k], At[m][k], acc[ai][bj][m][n], 0, 0, 0); __builtin_amdgcn_s_setprio(0); } while (0)
; #define PG8_WAIT_V(n) asm volatile("s_waitcnt vmcnt(" #n ")" ::: "memory")
; #define PG8_WAIT_L(n) asm volatile("s_waitcnt lgkmcnt(" #n ")" ::: "memory")
; #define PG8_BAR __builtin_amdgcn_s_barrier()
; #define PG8_SCHED __builtin_amdgcn_sched_barrier(0)
; template <class Epi, class Sched, bool ALIGN_EPI, bool SP2>
; __device__ __forceinline__ void gemm_phase(LAS unsigned char* lds, const int K, const Sched& S, const Epi& E) {
;     ...
;             PG8_LDB(B0, 0, 0); PG8_LDB(B1, 0, 1); PG8_SCHED; PG8_LDA(At, 0, 0); PG8_STAGE(PG8_SA(1, 1), a1 + hstep, voffA);
;             PG8_WAIT_V(8); PG8_WAIT_L(0); PG8_BAR; PG8_MMA(0, 0, At, B0); PG8_MMA(0, 1, At, B1); PG8_BAR; PG8_SCHED;
;             PG8_LDA(At, 0, 1); PG8_STAGE(PG8_SB(0, 0), b2, voffB); PG8_STAGE(PG8_SB(0, 1), b2 + hstep, voffB); PG8_STAGE(PG8_SA(0, 0), a2, voffA);
;             PG8_WAIT_V(8); PG8_WAIT_L(0); PG8_BAR; PG8_MMA(1, 0, At, B0); PG8_MMA(1, 1, At, B1); PG8_BAR; PG8_SCHED;
.LBB0_1082:
	v_add_u32_e32 v94, 0x10000, v155
	v_add_u32_e32 v150, 0x14000, v155
	ds_read_b128 v[74:77], v94
	ds_read_b128 v[86:89], v94 offset:1024
	ds_read_b128 v[90:93], v94 offset:2048
	ds_read_b128 v[94:97], v94 offset:3072
	ds_read_b128 v[146:149], v150
	ds_read_b128 v[158:161], v150 offset:1024
	ds_read_b128 v[162:165], v150 offset:2048
	ds_read_b128 v[166:169], v150 offset:3072
	s_cmpk_eq_i32 s51, 0x54
	s_cselect_b32 s24, s16, s46
	s_cselect_b32 s25, s17, s47
	s_cselect_b32 s34, s18, s48
	s_cselect_b32 s35, s19, s49
	s_add_u32 s26, s24, 0x80
	s_addc_u32 s27, s25, 0
	ds_read_b128 v[170:173], v156
	ds_read_b128 v[174:177], v156 offset:1024
	ds_read_b128 v[182:185], v156 offset:2048
	ds_read_b128 v[186:189], v156 offset:3072
	ds_read_b128 v[190:193], v156 offset:4096
	ds_read_b128 v[194:197], v156 offset:5120
	ds_read_b128 v[198:201], v156 offset:6144
	ds_read_b128 v[214:217], v156 offset:7168
	s_mov_b32 m0, s39
	s_nop 0
	global_load_lds_dwordx4 v0, s[22:23] nt
	s_mov_b32 m0, s40
	s_nop 0
	global_load_lds_dwordx4 v152, s[22:23] nt
	s_waitcnt vmcnt(8)
	s_waitcnt lgkmcnt(0)
	s_barrier
	s_setprio 1
	s_waitcnt lgkmcnt(7)
	v_mfma_f32_16x16x32_bf16 v[142:145], v[74:77], v[170:173], v[142:145]
	v_mfma_f32_16x16x32_bf16 v[138:141], v[90:93], v[170:173], v[138:141]
	s_waitcnt lgkmcnt(5)
	v_mfma_f32_16x16x32_bf16 v[126:129], v[74:77], v[182:185], v[126:129]
	v_mfma_f32_16x16x32_bf16 v[122:125], v[90:93], v[182:185], v[122:125]
	s_waitcnt lgkmcnt(3)
	v_mfma_f32_16x16x32_bf16 v[110:113], v[74:77], v[190:193], v[110:113]
	v_mfma_f32_16x16x32_bf16 v[106:109], v[90:93], v[190:193], v[106:109]
	s_waitcnt lgkmcnt(1)
	v_mfma_f32_16x16x32_bf16 v[82:85], v[74:77], v[198:201], v[82:85]
	v_mfma_f32_16x16x32_bf16 v[78:81], v[90:93], v[198:201], v[78:81]
	v_mfma_f32_16x16x32_bf16 v[142:145], v[86:89], v[174:177], v[142:145]
	v_mfma_f32_16x16x32_bf16 v[138:141], v[94:97], v[174:177], v[138:141]
	v_mfma_f32_16x16x32_bf16 v[126:129], v[86:89], v[186:189], v[126:129]
	v_mfma_f32_16x16x32_bf16 v[122:125], v[94:97], v[186:189], v[122:125]
	v_mfma_f32_16x16x32_bf16 v[110:113], v[86:89], v[194:197], v[110:113]
	v_mfma_f32_16x16x32_bf16 v[106:109], v[94:97], v[194:197], v[106:109]
	s_waitcnt lgkmcnt(0)
	v_mfma_f32_16x16x32_bf16 v[82:85], v[86:89], v[214:217], v[82:85]
	v_mfma_f32_16x16x32_bf16 v[78:81], v[94:97], v[214:217], v[78:81]
	s_setprio 0
	s_setprio 1
	v_mfma_f32_16x16x32_bf16 v[134:137], v[146:149], v[170:173], v[134:137]
	v_mfma_f32_16x16x32_bf16 v[130:133], v[162:165], v[170:173], v[130:133]
	v_mfma_f32_16x16x32_bf16 v[118:121], v[146:149], v[182:185], v[118:121]
	v_mfma_f32_16x16x32_bf16 v[114:117], v[162:165], v[182:185], v[114:117]
	v_mfma_f32_16x16x32_bf16 v[102:105], v[146:149], v[190:193], v[102:105]
	v_mfma_f32_16x16x32_bf16 v[98:101], v[162:165], v[190:193], v[98:101]
	v_mfma_f32_16x16x32_bf16 v[70:73], v[146:149], v[198:201], v[70:73]
	v_mfma_f32_16x16x32_bf16 v[66:69], v[162:165], v[198:201], v[66:69]
	v_mfma_f32_16x16x32_bf16 v[134:137], v[158:161], v[174:177], v[134:137]
	v_mfma_f32_16x16x32_bf16 v[130:133], v[166:169], v[174:177], v[130:133]
	v_mfma_f32_16x16x32_bf16 v[118:121], v[158:161], v[186:189], v[118:121]
	v_mfma_f32_16x16x32_bf16 v[114:117], v[166:169], v[186:189], v[114:117]
	v_mfma_f32_16x16x32_bf16 v[102:105], v[158:161], v[194:197], v[102:105]
	v_mfma_f32_16x16x32_bf16 v[98:101], v[166:169], v[194:197], v[98:101]
	v_mfma_f32_16x16x32_bf16 v[70:73], v[158:161], v[214:217], v[70:73]
	v_mfma_f32_16x16x32_bf16 v[66:69], v[166:169], v[214:217], v[66:69]
	s_setprio 0
	s_barrier
	ds_read_b128 v[170:173], v156 offset:16384
	ds_read_b128 v[174:177], v156 offset:17408
	ds_read_b128 v[182:185], v156 offset:18432
	ds_read_b128 v[186:189], v156 offset:19456
	ds_read_b128 v[190:193], v156 offset:20480
	ds_read_b128 v[194:197], v156 offset:21504
	ds_read_b128 v[198:201], v156 offset:22528
	ds_read_b128 v[214:217], v156 offset:23552
	s_mov_b32 m0, s5
	s_nop 0
	global_load_lds_dwordx4 v0, s[34:35]
	s_mov_b32 m0, s6
	s_nop 0
	global_load_lds_dwordx4 v152, s[34:35]
	s_add_u32 s52, s34, 0x160000
	s_addc_u32 s53, s35, 0
	s_mov_b32 m0, s7
	s_nop 0
	global_load_lds_dwordx4 v0, s[52:53]
	s_mov_b32 m0, s8
	s_nop 0
	global_load_lds_dwordx4 v152, s[52:53]
	s_mov_b32 m0, s4
	s_nop 0
	global_load_lds_dwordx4 v0, s[24:25] nt
	s_mov_b32 m0, s9
	s_nop 0
	global_load_lds_dwordx4 v152, s[24:25] nt
	s_waitcnt vmcnt(8)
	s_waitcnt lgkmcnt(0)
	s_barrier
	s_setprio 1
	s_waitcnt lgkmcnt(7)
	v_mfma_f32_16x16x32_bf16 v[62:65], v[74:77], v[170:173], v[62:65]
	v_mfma_f32_16x16x32_bf16 v[58:61], v[90:93], v[170:173], v[58:61]
	s_waitcnt lgkmcnt(5)
	v_mfma_f32_16x16x32_bf16 v[46:49], v[74:77], v[182:185], v[46:49]
	v_mfma_f32_16x16x32_bf16 v[42:45], v[90:93], v[182:185], v[42:45]
	s_waitcnt lgkmcnt(3)
	v_mfma_f32_16x16x32_bf16 v[30:33], v[74:77], v[190:193], v[30:33]
	v_mfma_f32_16x16x32_bf16 v[26:29], v[90:93], v[190:193], v[26:29]
	s_waitcnt lgkmcnt(1)
	v_mfma_f32_16x16x32_bf16 v[14:17], v[74:77], v[198:201], v[14:17]
	v_mfma_f32_16x16x32_bf16 v[10:13], v[90:93], v[198:201], v[10:13]
	v_mfma_f32_16x16x32_bf16 v[62:65], v[86:89], v[174:177], v[62:65]
	v_mfma_f32_16x16x32_bf16 v[58:61], v[94:97], v[174:177], v[58:61]
	v_mfma_f32_16x16x32_bf16 v[46:49], v[86:89], v[186:189], v[46:49]
	v_mfma_f32_16x16x32_bf16 v[42:45], v[94:97], v[186:189], v[42:45]
	v_mfma_f32_16x16x32_bf16 v[30:33], v[86:89], v[194:197], v[30:33]
	v_mfma_f32_16x16x32_bf16 v[26:29], v[94:97], v[194:197], v[26:29]
	s_waitcnt lgkmcnt(0)
	v_mfma_f32_16x16x32_bf16 v[14:17], v[86:89], v[214:217], v[14:17]
	v_mfma_f32_16x16x32_bf16 v[10:13], v[94:97], v[214:217], v[10:13]
	s_setprio 0
	s_setprio 1
	v_mfma_f32_16x16x32_bf16 v[54:57], v[146:149], v[170:173], v[54:57]
	v_mfma_f32_16x16x32_bf16 v[50:53], v[162:165], v[170:173], v[50:53]
	v_mfma_f32_16x16x32_bf16 v[38:41], v[146:149], v[182:185], v[38:41]
	v_mfma_f32_16x16x32_bf16 v[34:37], v[162:165], v[182:185], v[34:37]
	v_mfma_f32_16x16x32_bf16 v[22:25], v[146:149], v[190:193], v[22:25]
	v_mfma_f32_16x16x32_bf16 v[18:21], v[162:165], v[190:193], v[18:21]
	v_mfma_f32_16x16x32_bf16 v[6:9], v[146:149], v[198:201], v[6:9]
	v_mfma_f32_16x16x32_bf16 v[2:5], v[162:165], v[198:201], v[2:5]
	v_mfma_f32_16x16x32_bf16 v[54:57], v[158:161], v[174:177], v[54:57]
	v_mfma_f32_16x16x32_bf16 v[50:53], v[166:169], v[174:177], v[50:53]
	v_mfma_f32_16x16x32_bf16 v[38:41], v[158:161], v[186:189], v[38:41]
	v_mfma_f32_16x16x32_bf16 v[34:37], v[166:169], v[186:189], v[34:37]
	v_mfma_f32_16x16x32_bf16 v[22:25], v[158:161], v[194:197], v[22:25]
	v_mfma_f32_16x16x32_bf16 v[18:21], v[166:169], v[194:197], v[18:21]
	v_mfma_f32_16x16x32_bf16 v[6:9], v[158:161], v[214:217], v[6:9]
	v_mfma_f32_16x16x32_bf16 v[2:5], v[166:169], v[214:217], v[2:5]
	s_setprio 0
	s_barrier
; #define PG8_STAGE(bufoff, gbase, voff) do { _Pragma("unroll") for (int _i = 0; _i < 2; ++_i) \
;         glds_s((voff)[_i], (const void*)(gbase), ldsbase + (unsigned)((bufoff) + _i * 8192)); } while (0)
; #define PG8_LDA(dst, b, h) do { _Pragma("unroll") for (int m = 0; m < 4; ++m) _Pragma("unroll") for (int k = 0; k < 2; ++k) dst[m][k] = *(const LAS bf16x8*)(lds + PG8_SA(b, h) + aoff + m * 2048 + k * 1024); } while (0)
; #define PG8_LDB(dst, b, h) do { _Pragma("unroll") for (int n = 0; n < 2; ++n) _Pragma("unroll") for (int k = 0; k < 2; ++k) dst[n][k] = *(const LAS bf16x8*)(lds + PG8_SB(b, h) + boff + n * 2048 + k * 1024); } while (0)
; #define PG8_MMA(ai, bj, At, Bt) do { __builtin_amdgcn_s_setprio(1); _Pragma("unroll") for (int m = 0; m < 4; ++m) _Pragma("unroll") for (int n = 0; n < 2; ++n) _Pragma("unroll") for (int k = 0; k < 2; ++k) \
;         acc[ai][bj][m][n] = __builtin_amdgcn_mfma_f32_16x16x32_bf16(Bt[n][k], At[m][k], acc[ai][bj][m][n], 0, 0, 0); __builtin_amdgcn_s_setprio(0); } while (0)
; #define PG8_WAIT_V(n) asm volatile("s_waitcnt vmcnt(" #n ")" ::: "memory")
; #define PG8_WAIT_L(n) asm volatile("s_waitcnt lgkmcnt(" #n ")" ::: "memory")
; #define PG8_BAR __builtin_amdgcn_s_barrier()
; #define PG8_SCHED __builtin_amdgcn_sched_barrier(0)
; template <class Epi, class Sched, bool ALIGN_EPI, bool SP2>
; __device__ __forceinline__ void gemm_phase(LAS unsigned char* lds, const int K, const Sched& S, const Epi& E) {
;     ...
;         const bool has_next = S.next(ui + 1, nxt);
;         const char* nA = has_next ? nxt.A : cA; const char* nB = has_next ? nxt.B : cB;
;         for (int t = 0; t < nt; t += 2) {
;             const bool last = (t == nt - 2);
;             const char* a1 = cA + (size_t)(t + 1) * kstep;
;             const char* a2 = last ? nA : cA + (size_t)(t + 2) * kstep; const char* b2 = last ? nB : cB + (size_t)(t + 2) * kstep;
;     ...
;             PG8_LDB(B0, 1, 0); PG8_LDB(B1, 1, 1); PG8_SCHED; PG8_LDA(At, 1, 0); PG8_STAGE(PG8_SA(0, 1), a2 + hstep, voffA);
;             PG8_WAIT_V(8); PG8_WAIT_L(0); PG8_BAR; PG8_MMA(0, 0, At, B0); PG8_MMA(0, 1, At, B1); PG8_BAR; PG8_SCHED;
;             PG8_LDA(At, 1, 1); PG8_STAGE(PG8_SB(1, 0), b3, voffB); PG8_STAGE(PG8_SB(1, 1), b3 + hstep, voffB); PG8_STAGE(PG8_SA(1, 0), a3, voffA);
;             PG8_WAIT_V(8); PG8_WAIT_L(0); PG8_BAR; PG8_MMA(1, 0, At, B0); PG8_MMA(1, 1, At, B1); PG8_BAR; PG8_SCHED;
	v_add_u32_e32 v94, 0x18000, v155
	v_add_u32_e32 v150, 0x1c000, v155
	ds_read_b128 v[74:77], v94
	ds_read_b128 v[86:89], v94 offset:1024
	ds_read_b128 v[90:93], v94 offset:2048
	ds_read_b128 v[94:97], v94 offset:3072
	ds_read_b128 v[146:149], v150
	ds_read_b128 v[158:161], v150 offset:1024
	ds_read_b128 v[162:165], v150 offset:2048
	ds_read_b128 v[166:169], v150 offset:3072
	ds_read_b128 v[170:173], v156 offset:32768
	ds_read_b128 v[174:177], v156 offset:33792
	ds_read_b128 v[182:185], v156 offset:34816
	ds_read_b128 v[186:189], v156 offset:35840
	ds_read_b128 v[190:193], v156 offset:36864
	ds_read_b128 v[194:197], v156 offset:37888
	ds_read_b128 v[198:201], v156 offset:38912
	ds_read_b128 v[214:217], v156 offset:39936
	s_add_u32 s24, s24, 0x160000
	s_addc_u32 s25, s25, 0
	s_mov_b32 m0, s10
	s_nop 0
	global_load_lds_dwordx4 v0, s[24:25] nt
	s_mov_b32 m0, s11
	s_nop 0
	global_load_lds_dwordx4 v152, s[24:25] nt
	s_waitcnt vmcnt(8)
	s_waitcnt lgkmcnt(0)
	s_barrier
	s_setprio 1
	s_waitcnt lgkmcnt(7)
	v_mfma_f32_16x16x32_bf16 v[142:145], v[74:77], v[170:173], v[142:145]
	v_mfma_f32_16x16x32_bf16 v[138:141], v[90:93], v[170:173], v[138:141]
	s_waitcnt lgkmcnt(5)
	v_mfma_f32_16x16x32_bf16 v[126:129], v[74:77], v[182:185], v[126:129]
	v_mfma_f32_16x16x32_bf16 v[122:125], v[90:93], v[182:185], v[122:125]
	s_waitcnt lgkmcnt(3)
	v_mfma_f32_16x16x32_bf16 v[110:113], v[74:77], v[190:193], v[110:113]
	v_mfma_f32_16x16x32_bf16 v[106:109], v[90:93], v[190:193], v[106:109]
	s_waitcnt lgkmcnt(1)
	v_mfma_f32_16x16x32_bf16 v[82:85], v[74:77], v[198:201], v[82:85]
	v_mfma_f32_16x16x32_bf16 v[78:81], v[90:93], v[198:201], v[78:81]
	v_mfma_f32_16x16x32_bf16 v[142:145], v[86:89], v[174:177], v[142:145]
	v_mfma_f32_16x16x32_bf16 v[138:141], v[94:97], v[174:177], v[138:141]
	v_mfma_f32_16x16x32_bf16 v[126:129], v[86:89], v[186:189], v[126:129]
	v_mfma_f32_16x16x32_bf16 v[122:125], v[94:97], v[186:189], v[122:125]
	v_mfma_f32_16x16x32_bf16 v[110:113], v[86:89], v[194:197], v[110:113]
	v_mfma_f32_16x16x32_bf16 v[106:109], v[94:97], v[194:197], v[106:109]
	s_waitcnt lgkmcnt(0)
	v_mfma_f32_16x16x32_bf16 v[82:85], v[86:89], v[214:217], v[82:85]
	v_mfma_f32_16x16x32_bf16 v[78:81], v[94:97], v[214:217], v[78:81]
	s_setprio 0
	s_setprio 1
	v_mfma_f32_16x16x32_bf16 v[134:137], v[146:149], v[170:173], v[134:137]
	v_mfma_f32_16x16x32_bf16 v[130:133], v[162:165], v[170:173], v[130:133]
	v_mfma_f32_16x16x32_bf16 v[118:121], v[146:149], v[182:185], v[118:121]
	v_mfma_f32_16x16x32_bf16 v[114:117], v[162:165], v[182:185], v[114:117]
	v_mfma_f32_16x16x32_bf16 v[102:105], v[146:149], v[190:193], v[102:105]
	v_mfma_f32_16x16x32_bf16 v[98:101], v[162:165], v[190:193], v[98:101]
	v_mfma_f32_16x16x32_bf16 v[70:73], v[146:149], v[198:201], v[70:73]
	v_mfma_f32_16x16x32_bf16 v[66:69], v[162:165], v[198:201], v[66:69]
	v_mfma_f32_16x16x32_bf16 v[134:137], v[158:161], v[174:177], v[134:137]
	v_mfma_f32_16x16x32_bf16 v[130:133], v[166:169], v[174:177], v[130:133]
	v_mfma_f32_16x16x32_bf16 v[118:121], v[158:161], v[186:189], v[118:121]
	v_mfma_f32_16x16x32_bf16 v[114:117], v[166:169], v[186:189], v[114:117]
	v_mfma_f32_16x16x32_bf16 v[102:105], v[158:161], v[194:197], v[102:105]
	v_mfma_f32_16x16x32_bf16 v[98:101], v[166:169], v[194:197], v[98:101]
	v_mfma_f32_16x16x32_bf16 v[70:73], v[158:161], v[214:217], v[70:73]
	v_mfma_f32_16x16x32_bf16 v[66:69], v[166:169], v[214:217], v[66:69]
	s_setprio 0
	s_barrier
	ds_read_b128 v[170:173], v156 offset:49152
	ds_read_b128 v[174:177], v156 offset:50176
	ds_read_b128 v[182:185], v156 offset:51200
	ds_read_b128 v[186:189], v156 offset:52224
	ds_read_b128 v[190:193], v156 offset:53248
	ds_read_b128 v[194:197], v156 offset:54272
	ds_read_b128 v[198:201], v156 offset:55296
	ds_read_b128 v[214:217], v156 offset:56320
	s_add_u32 s24, s34, 0x80
	s_addc_u32 s25, s35, 0
	s_mov_b32 m0, s28
	s_nop 0
	global_load_lds_dwordx4 v0, s[24:25]
	s_mov_b32 m0, s30
	s_nop 0
	global_load_lds_dwordx4 v152, s[24:25]
	s_add_u32 s24, s34, 0x160080
	s_addc_u32 s25, s35, 0
	s_mov_b32 m0, s37
	s_nop 0
	global_load_lds_dwordx4 v0, s[24:25]
	s_mov_b32 m0, s38
	s_nop 0
	global_load_lds_dwordx4 v152, s[24:25]
	s_mov_b32 m0, s31
	s_nop 0
	global_load_lds_dwordx4 v0, s[26:27] nt
	s_mov_b32 m0, s36
	s_nop 0
	global_load_lds_dwordx4 v152, s[26:27] nt
	s_waitcnt vmcnt(8)
	s_waitcnt lgkmcnt(0)
	s_barrier
	s_setprio 1
	s_waitcnt lgkmcnt(7)
	v_mfma_f32_16x16x32_bf16 v[62:65], v[74:77], v[170:173], v[62:65]
	v_mfma_f32_16x16x32_bf16 v[58:61], v[90:93], v[170:173], v[58:61]
	s_waitcnt lgkmcnt(5)
	v_mfma_f32_16x16x32_bf16 v[46:49], v[74:77], v[182:185], v[46:49]
	v_mfma_f32_16x16x32_bf16 v[42:45], v[90:93], v[182:185], v[42:45]
	s_waitcnt lgkmcnt(3)
	v_mfma_f32_16x16x32_bf16 v[30:33], v[74:77], v[190:193], v[30:33]
	v_mfma_f32_16x16x32_bf16 v[26:29], v[90:93], v[190:193], v[26:29]
	s_waitcnt lgkmcnt(1)
	v_mfma_f32_16x16x32_bf16 v[14:17], v[74:77], v[198:201], v[14:17]
	v_mfma_f32_16x16x32_bf16 v[10:13], v[90:93], v[198:201], v[10:13]
	v_mfma_f32_16x16x32_bf16 v[62:65], v[86:89], v[174:177], v[62:65]
	v_mfma_f32_16x16x32_bf16 v[58:61], v[94:97], v[174:177], v[58:61]
	v_mfma_f32_16x16x32_bf16 v[46:49], v[86:89], v[186:189], v[46:49]
	v_mfma_f32_16x16x32_bf16 v[42:45], v[94:97], v[186:189], v[42:45]
	v_mfma_f32_16x16x32_bf16 v[30:33], v[86:89], v[194:197], v[30:33]
	v_mfma_f32_16x16x32_bf16 v[26:29], v[94:97], v[194:197], v[26:29]
	s_waitcnt lgkmcnt(0)
	v_mfma_f32_16x16x32_bf16 v[14:17], v[86:89], v[214:217], v[14:17]
	v_mfma_f32_16x16x32_bf16 v[10:13], v[94:97], v[214:217], v[10:13]
	s_setprio 0
	s_setprio 1
	v_mfma_f32_16x16x32_bf16 v[54:57], v[146:149], v[170:173], v[54:57]
	v_mfma_f32_16x16x32_bf16 v[50:53], v[162:165], v[170:173], v[50:53]
	v_mfma_f32_16x16x32_bf16 v[38:41], v[146:149], v[182:185], v[38:41]
	v_mfma_f32_16x16x32_bf16 v[34:37], v[162:165], v[182:185], v[34:37]
	v_mfma_f32_16x16x32_bf16 v[22:25], v[146:149], v[190:193], v[22:25]
	v_mfma_f32_16x16x32_bf16 v[18:21], v[162:165], v[190:193], v[18:21]
	v_mfma_f32_16x16x32_bf16 v[6:9], v[146:149], v[198:201], v[6:9]
	v_mfma_f32_16x16x32_bf16 v[2:5], v[162:165], v[198:201], v[2:5]
	v_mfma_f32_16x16x32_bf16 v[54:57], v[158:161], v[174:177], v[54:57]
	v_mfma_f32_16x16x32_bf16 v[50:53], v[166:169], v[174:177], v[50:53]
	v_mfma_f32_16x16x32_bf16 v[38:41], v[158:161], v[186:189], v[38:41]
	v_mfma_f32_16x16x32_bf16 v[34:37], v[166:169], v[186:189], v[34:37]
	v_mfma_f32_16x16x32_bf16 v[22:25], v[158:161], v[194:197], v[22:25]
	v_mfma_f32_16x16x32_bf16 v[18:21], v[166:169], v[194:197], v[18:21]
	v_mfma_f32_16x16x32_bf16 v[6:9], v[158:161], v[214:217], v[6:9]
	v_mfma_f32_16x16x32_bf16 v[2:5], v[166:169], v[214:217], v[2:5]
	s_setprio 0
	s_barrier
	s_add_i32 s51, s51, 2
	s_add_u32 s46, s46, 0x100
	s_addc_u32 s47, s47, 0
	s_add_u32 s48, s48, 0x100
	s_addc_u32 s49, s49, 0
	s_add_u32 s22, s22, 0x100
	s_addc_u32 s23, s23, 0
	s_cmpk_gt_u32 s51, 0x55
	s_cbranch_scc0 .LBB0_1082
	v_readlane_b32 s46, v250, 8
	s_and_b64 vcc, exec, s[12:13]
	v_readlane_b32 s47, v250, 9
	s_cbranch_vccz .LBB0_1085
	s_barrier
